# load balance: combine work done only by the workgroups with 9 in-proj tiles in merged phases
# speedup vs baseline: 1.0079x; 1.0079x over previous
; #define LAS __attribute__((address_space(3)))
; #define LAUNDER_S(x) asm volatile("" : "+s"(x))
; __global__ void __launch_bounds__(512) fwd_megakernel(Params P) {
;   extern __shared__ __attribute__((aligned(16))) unsigned char shm[];
;   LAS unsigned char* lds = (LAS unsigned char*)shm;
;   cg::grid_group grid = cg::this_grid();
;   if (blockIdx.x == 0 && threadIdx.x == 0) __hip_atomic_store((unsigned*)(P.ws + O_CTR), 0u, __ATOMIC_RELAXED, __HIP_MEMORY_SCOPE_AGENT);
;   for (int ph = P.ph_lo; ph < P.ph_hi; ++ph) {
;     unsigned char* ws = P.ws; LAUNDER_S(ws);
_Z14fwd_megakernel6Params:
	s_load_dwordx4 s[4:7], s[0:1], 0xc0
	s_mov_b32 s8, s2
	s_load_dwordx2 s[2:3], s[0:1], 0xd0
	v_and_b32_e32 v215, 0x3ff, v0
	v_or_b32_e32 v1, s8, v215
	s_waitcnt lgkmcnt(0)
	v_writelane_b32 v253, s4, 0
	v_cmp_eq_u32_e32 vcc, 0, v1
	s_nop 0
	v_writelane_b32 v253, s5, 1
	v_writelane_b32 v253, s6, 2
	v_writelane_b32 v253, s7, 3
	v_writelane_b32 v253, s2, 4
	s_nop 1
	v_writelane_b32 v253, s3, 5
	s_load_dword s3, s[0:1], 0xd8
	s_add_u32 s2, s0, 0xd8
	s_waitcnt lgkmcnt(0)
	v_writelane_b32 v253, s3, 6
	v_writelane_b32 v255, s3, 49
	s_addc_u32 s3, s1, 0
	v_writelane_b32 v253, s2, 7
	s_nop 1
	v_writelane_b32 v253, s3, 8
	v_writelane_b32 v253, s8, 9
	v_writelane_b32 v255, s8, 50
	v_writelane_b32 v255, 0, 48
	v_writelane_b32 v255, 0, 60
	v_writelane_b32 v255, 1, 59
	v_writelane_b32 v255, 0, 58
	v_writelane_b32 v255, 0, 57
	s_and_saveexec_b64 s[4:5], vcc
	s_cbranch_execz .LBB0_2
	s_load_dwordx4 s[8:11], s[0:1], 0xc0
	v_mov_b32_e32 v1, 0x3f912000
	v_mov_b32_e32 v2, 0
	s_waitcnt lgkmcnt(0)
	global_store_dword v1, v2, s[10:11] sc1

; #define LAS __attribute__((address_space(3)))
; #define GAS __attribute__((address_space(1)))
; #define LAUNDER_V(x) asm volatile("" : "+v"(x))
; #define LAUNDER_S(x) asm volatile("" : "+s"(x))
; __device__ __forceinline__ void phase_combine(const Params& P, int slice, LAS unsigned char* lds) {
;   unsigned char* ws = P.ws; LAUNDER_S(ws); int tid = threadIdx.x; LAUNDER_V(tid); const int bid = blockIdx.x, G = gridDim.x;
;   const GAS float* lse = (const GAS float*)(ws + O_LSE); const GAS u16* o3 = (const GAS u16*)(ws + O_O3); GAS u16* att = (GAS u16*)(ws + O_ATT);
;   const int Lc = slice < 4 ? 2048 : 16384;
;   for (int idx0 = bid * 512 + tid; idx0 < TS * 64; idx0 += 2 * G * 512) {
;     float l[2][3]; u32x4 ov[2][3]; int tokv[2], chv[2]; bool ok[2];
; #pragma unroll
;     for (int r = 0; r < 2; ++r) {
;       int idx = idx0 + r * G * 512; ok[r] = idx < TS * 64; idx = ok[r] ? idx : idx0;
;       const int tok = idx >> 6, ch = idx & 63, g = ch >> 4; tokv[r] = tok; chv[r] = ch;
;       const int tl = tok & (Lc - 1), tb = tok - tl;
;       l[r][0] = lse[(size_t)(0 + g) * TS + tok];
;       l[r][1] = lse[(size_t)(4 + g) * TS + tb + (tl & 3) * (Lc >> 2) + (tl >> 2)];
;       l[r][2] = lse[(size_t)(8 + g) * TS + tb + (tl & 15) * (Lc >> 4) + (tl >> 4)];
; #pragma unroll
;       for (int gi = 0; gi < 3; ++gi) ov[r][gi] = *(const GAS u32x4*)(o3 + ((size_t)gi * TS + tok) * 512 + ch * 8);
;     }
.LBB0_353:
	s_and_b64 vcc, exec, s[4:5]
	s_cbranch_vccz .LBB0_376
	s_cmp_gt_u32 s72, 12
	s_cbranch_scc1 .Lcmb_noremap
	v_readlane_b32 s0, v255, 50
	v_readlane_b32 s1, v255, 49
	s_nop 0
	s_lshr_b32 s1, s1, 1
	s_cmp_lt_u32 s0, s1
	s_cbranch_scc1 .LBB0_376
	s_sub_i32 s0, s0, s1
	v_writelane_b32 v253, s0, 9
	s_lshl_b32 s2, s0, 9
	v_writelane_b32 v253, s2, 12
	s_lshl_b32 s2, s0, 6
	v_writelane_b32 v253, s2, 35
	v_writelane_b32 v253, s1, 6
	s_lshl_b32 s2, s1, 3
	v_writelane_b32 v253, s2, 20
	s_lshl_b32 s2, s1, 1
	v_writelane_b32 v253, s2, 33
	s_lshl_b32 s2, s1, 2
	v_writelane_b32 v253, s2, 36
	s_lshl_b32 s2, s1, 6
	v_writelane_b32 v253, s2, 38
	s_lshl_b32 s2, s1, 7
	v_writelane_b32 v253, s2, 34
	s_lshl_b32 s2, s1, 8
	v_writelane_b32 v253, s2, 37
	s_lshl_b32 s73, s1, 9
	v_writelane_b32 v255, 1, 48
	s_nop 1
.Lcmb_noremap:
	v_readlane_b32 s0, v253, 0
	v_readlane_b32 s2, v253, 2
	v_readlane_b32 s3, v253, 3
	s_mov_b64 s[4:5], s[2:3]
	v_mov_b32_e32 v24, v215
	v_readlane_b32 s0, v253, 12
	v_readlane_b32 s1, v253, 1
	s_nop 0
	v_add_u32_e32 v0, s0, v24
	s_mov_b32 s0, 0x100000
	v_cmp_gt_i32_e32 vcc, s0, v0
	s_and_saveexec_b64 s[6:7], vcc
	s_cbranch_execz .LBB0_359
	s_add_u32 s8, s4, 0x30852000
	s_addc_u32 s9, s5, 0
	s_add_u32 s10, s4, 0x2d852000
	s_addc_u32 s11, s5, 0
	s_add_u32 s12, s4, 0x30912000
	s_addc_u32 s13, s5, 0
	v_lshlrev_b32_e32 v2, 12, v24
	s_cmp_lt_u32 s74, 12
	s_movk_i32 s0, 0x7ff
	s_waitcnt lgkmcnt(0)
	v_and_b32_e32 v80, 0x30000, v2
	s_cselect_b32 s2, s0, 0x3fff
	v_and_b32_e32 v1, 63, v24
	v_lshl_add_u64 v[12:13], s[8:9], 0, v[80:81]
	s_mov_b64 s[0:1], 0x40000
	v_lshl_add_u64 v[14:15], v[12:13], 0, s[0:1]
	s_mov_b64 s[0:1], 0x80000
	v_lshlrev_b32_e32 v80, 4, v1
	s_cselect_b32 s3, 9, 12
	s_cselect_b32 s16, 7, 10
	v_lshl_add_u64 v[16:17], v[12:13], 0, s[0:1]
	v_lshl_add_u64 v[18:19], s[10:11], 0, v[80:81]
	v_lshl_add_u64 v[20:21], s[12:13], 0, v[80:81]
	s_mov_b64 s[14:15], 0
	s_branch .LBB0_357

; #define LAS __attribute__((address_space(3)))
; #define LAUNDER_V(x) asm volatile("" : "+v"(x))
; #define LAUNDER_S(x) asm volatile("" : "+s"(x))
; __device__ __forceinline__ void phase_combine(const Params& P, int slice, LAS unsigned char* lds) {
;   unsigned char* ws = P.ws; LAUNDER_S(ws); int tid = threadIdx.x; LAUNDER_V(tid); const int bid = blockIdx.x, G = gridDim.x;
.LBB0_376:
	v_readlane_b32 s0, v255, 48
	s_nop 0
	s_cmp_eq_u32 s0, 0
	s_cbranch_scc1 .Lcmb_norestore
	v_readlane_b32 s0, v255, 50
	v_readlane_b32 s1, v255, 49
	s_nop 0
	v_writelane_b32 v253, s0, 9
	s_lshl_b32 s2, s0, 9
	v_writelane_b32 v253, s2, 12
	s_lshl_b32 s2, s0, 6
	v_writelane_b32 v253, s2, 35
	v_writelane_b32 v253, s1, 6
	s_lshl_b32 s2, s1, 3
	v_writelane_b32 v253, s2, 20
	s_lshl_b32 s2, s1, 1
	v_writelane_b32 v253, s2, 33
	s_lshl_b32 s2, s1, 2
	v_writelane_b32 v253, s2, 36
	s_lshl_b32 s2, s1, 6
	v_writelane_b32 v253, s2, 38
	s_lshl_b32 s2, s1, 7
	v_writelane_b32 v253, s2, 34
	s_lshl_b32 s2, s1, 8
	v_writelane_b32 v253, s2, 37
	s_lshl_b32 s73, s1, 9
	v_writelane_b32 v255, 0, 48
	s_nop 1
